# G1 task: the eight value-chunk loads issued with the key-chunk loads instead of behind two workgroup barriers; waits recounted
# baseline (speedup 1.0000x reference)
; __device__ __forceinline__ bf16_t f2bf(float f) { return (bf16_t)f2bf_u(f); }
; __device__ __forceinline__ float bf_lo(unsigned u) { return __uint_as_float(u << 16); }
; __device__ __forceinline__ float bf_hi(unsigned u) { return __uint_as_float(u & 0xffff0000u); }
; __device__ void phaseG1_task(const Params& p, int task, char* lds) {
;     ...
;     if (tid < 128) ((float*)(p.ws + OFF_DEC))[task * 128 + tid] = __expf(bc[63 * 128 + tid]);
;     {
;         f32x4* bg = (f32x4*)(p.ws + OFF_M) + (size_t)task * 2048;
; #pragma unroll
;         for (int i = 0; i < 8; i++) bg[i * 256 + tid] = ((const f32x4*)bc)[i * 256 + tid];
;     }
;     {
;         const int s = lane, dc = wave * 32;
;         const bf16_t* kp = Z + (size_t)(tok0 + s) * ZC + ZK_G + h * 128 + dc;
; #pragma unroll
;         for (int v4 = 0; v4 < 4; v4++) {
;             const u32x4 kv = *(const u32x4*)(kp + v4 * 8);
;             const unsigned kw[4] = {kv.x, kv.y, kv.z, kv.w};
; #pragma unroll
;             for (int j = 0; j < 8; j++) {
;                 const int d = dc + v4 * 8 + j;
;                 const float kval = (j & 1) ? bf_hi(kw[j >> 1]) : bf_lo(kw[j >> 1]);
;                 klT[d * 72 + s] = f2bf(kval * __expf(bc[63 * 128 + d] - bc[s * 128 + d]));
;             }
;         }
;     }
;     for (int eh = 0; eh < 2; eh++) {
;         __syncthreads();
;         {
;             const int s = lane, ec = wave * 32;
;             const bf16_t* vp = Z + (size_t)(tok0 + s) * ZC + ZV_G + h * 256 + eh * 128 + ec;
; #pragma unroll
;             for (int v4 = 0; v4 < 4; v4++) {
;                 const u32x4 vv = *(const u32x4*)(vp + v4 * 8);
;                 const unsigned vw[4] = {vv.x, vv.y, vv.z, vv.w};
; #pragma unroll
;                 for (int j = 0; j < 8; j++) vT[(ec + v4 * 8 + j) * 72 + s] = (bf16_t)((j & 1) ? (vw[j >> 1] >> 16) : (vw[j >> 1] & 0xffffu));
;             }
.LBB0_378:
	s_or_b64 exec, exec, s[8:9]
	s_lshl_b32 s8, s14, 4
	s_lshl_b32 s9, s14, 6
	v_lshlrev_b32_e32 v8, 4, v0
	s_and_b32 s8, s8, 0xfffff800
	s_and_b32 s9, s9, 0x7c0
	s_ashr_i32 s15, s14, 31
	v_add_u32_e32 v10, s33, v8
	s_or_b32 s10, s8, s9
	s_lshl_b64 s[8:9], s[14:15], 15
	ds_read_b128 v[0:3], v10
	ds_read_b128 v[4:7], v10 offset:4096
	s_add_u32 s8, s6, s8
	s_addc_u32 s9, s7, s9
	s_add_u32 s8, s8, 0x3c00000
	s_addc_u32 s9, s9, 0
	s_waitcnt lgkmcnt(1)
	global_store_dwordx4 v8, v[0:3], s[8:9]
	ds_read_b128 v[0:3], v10 offset:8192
	v_or_b32_e32 v11, 0x1000, v8
	s_waitcnt lgkmcnt(1)
	global_store_dwordx4 v11, v[4:7], s[8:9]
	ds_read_b128 v[4:7], v10 offset:12288
	v_or_b32_e32 v11, 0x2000, v8
	s_waitcnt lgkmcnt(1)
	global_store_dwordx4 v11, v[0:3], s[8:9]
	ds_read_b128 v[0:3], v10 offset:16384
	v_or_b32_e32 v11, 0x3000, v8
	s_waitcnt lgkmcnt(1)
	global_store_dwordx4 v11, v[4:7], s[8:9]
	v_or_b32_e32 v11, 0x4000, v8
	ds_read_b128 v[4:7], v10 offset:20480
	s_waitcnt lgkmcnt(1)
	global_store_dwordx4 v11, v[0:3], s[8:9]
	ds_read_b128 v[0:3], v10 offset:24576
	ds_read_b128 v[14:17], v10 offset:28672
	v_or_b32_e32 v11, 0x5000, v8
	s_waitcnt lgkmcnt(2)
	global_store_dwordx4 v11, v[4:7], s[8:9]
	v_and_b32_e32 v18, 63, v12
	v_lshrrev_b32_e32 v13, 1, v12
	v_or_b32_e32 v4, 0x6000, v8
	s_waitcnt lgkmcnt(1)
	global_store_dwordx4 v4, v[0:3], s[8:9]
	s_lshl_b32 s18, s18, 1
	s_nop 0
	v_or_b32_e32 v0, 0x7000, v8
	s_waitcnt lgkmcnt(0)
	global_store_dwordx4 v0, v[14:17], s[8:9]
	v_or_b32_e32 v2, s10, v18
	v_mov_b64_e32 v[0:1], s[6:7]
	v_mad_i64_i32 v[0:1], s[6:7], v2, s38, v[0:1]
	v_and_b32_e32 v14, 0x60, v13
	v_lshl_add_u64 v[10:11], v[0:1], 0, s[20:21]
	v_lshl_add_u64 v[0:1], v[10:11], 0, s[18:19]
	v_lshlrev_b32_e32 v8, 1, v14
	v_lshl_add_u64 v[4:5], v[0:1], 0, v[8:9]
	global_load_dwordx4 v[22:25], v[4:5], off offset:1024
	global_load_dwordx4 v[26:29], v[4:5], off offset:1040
	v_lshl_add_u32 v16, v14, 2, s33
	v_lshl_add_u32 v17, v18, 9, v16
	ds_read_b128 v[30:33], v16 offset:32256
	ds_read_b128 v[34:37], v16 offset:32272
	ds_read_b128 v[38:41], v17
	v_mul_u32_u24_e32 v0, 0x48, v14
	ds_read_b128 v[42:45], v17 offset:16
	v_or_b32_e32 v1, 1, v14
	v_or_b32_e32 v0, v0, v18
	s_waitcnt lgkmcnt(1)
	v_sub_f32_e32 v30, v30, v38
	v_sub_f32_e32 v31, v31, v39
	v_sub_f32_e32 v32, v32, v40
	v_sub_f32_e32 v33, v33, v41
	v_mul_f32_e32 v30, 0x3fb8aa3b, v30
	v_mul_f32_e32 v31, 0x3fb8aa3b, v31
	v_mul_f32_e32 v32, 0x3fb8aa3b, v32
	v_mul_f32_e32 v33, 0x3fb8aa3b, v33
	v_exp_f32_e32 v30, v30
	v_exp_f32_e32 v31, v31
	v_exp_f32_e32 v32, v32
	v_exp_f32_e32 v33, v33
	v_lshlrev_b32_e32 v15, 1, v18
	v_mul_u32_u24_e32 v1, 0x90, v1
	v_lshl_add_u32 v21, v0, 1, s33
	v_add3_u32 v19, s33, v1, v15
	s_lshl_b32 s48, s47, 9
	s_mov_b32 s49, 0
	v_lshl_add_u64 v[164:165], v[10:11], 0, s[48:49]
	v_lshl_add_u64 v[164:165], v[164:165], 0, v[8:9]
	global_load_dwordx4 v[0:3], v[4:5], off offset:1072
	s_nop 0
	global_load_dwordx4 v[4:7], v[4:5], off offset:1056
	global_load_dwordx4 v[130:133], v[164:165], off offset:2048
	global_load_dwordx4 v[134:137], v[164:165], off offset:2064
	global_load_dwordx4 v[138:141], v[164:165], off offset:2080
	global_load_dwordx4 v[142:145], v[164:165], off offset:2096
	global_load_dwordx4 v[146:149], v[164:165], off offset:2304
	global_load_dwordx4 v[150:153], v[164:165], off offset:2320
	global_load_dwordx4 v[154:157], v[164:165], off offset:2336
	global_load_dwordx4 v[160:163], v[164:165], off offset:2352
	s_lshl_b32 s18, s47, 9
	s_lshl_b64 s[6:7], s[14:15], 16
	s_add_u32 s4, s4, s6
	s_addc_u32 s5, s5, s7
	s_add_i32 s14, s14, s0
	s_add_i32 s2, s2, s3
	s_add_i32 s36, s36, s37
	s_cmpk_gt_i32 s14, 0x3ff
	s_waitcnt vmcnt(11)
	v_lshlrev_b32_e32 v38, 16, v22
	v_and_b32_e32 v22, 0xffff0000, v22
	v_lshlrev_b32_e32 v39, 16, v23
	v_and_b32_e32 v23, 0xffff0000, v23
	v_mul_f32_e32 v30, v30, v38
	v_mul_f32_e32 v22, v31, v22
	v_mul_f32_e32 v31, v32, v39
	v_mul_f32_e32 v23, v33, v23
	v_bfe_u32 v32, v30, 16, 1
	v_bfe_u32 v33, v22, 16, 1
	v_bfe_u32 v38, v31, 16, 1
	v_add3_u32 v30, v30, v32, s46
	v_add3_u32 v22, v22, v33, s46
	v_add3_u32 v31, v31, v38, s46
	ds_write_b16_d16_hi v21, v30 offset:36864
	ds_write_b16_d16_hi v19, v22 offset:36864
	ds_write_b16_d16_hi v19, v31 offset:37008
	v_bfe_u32 v22, v23, 16, 1
	v_add3_u32 v22, v23, v22, s46
	ds_write_b16_d16_hi v19, v22 offset:37152
	s_waitcnt lgkmcnt(4)
	v_sub_f32_e32 v22, v34, v42
	v_mul_f32_e32 v22, 0x3fb8aa3b, v22
	v_exp_f32_e32 v22, v22
	v_lshlrev_b32_e32 v23, 16, v24
	v_sub_f32_e32 v34, v35, v43
	v_mul_f32_e32 v34, 0x3fb8aa3b, v34
	v_mul_f32_e32 v22, v22, v23
	v_bfe_u32 v23, v22, 16, 1
	v_exp_f32_e32 v34, v34
	v_add3_u32 v22, v22, v23, s46
	ds_read_b128 v[30:33], v16 offset:32288
	ds_read_b128 v[38:41], v17 offset:32
	ds_write_b16_d16_hi v19, v22 offset:37296
	v_and_b32_e32 v22, 0xffff0000, v24
	v_sub_f32_e32 v24, v36, v44
	v_mul_f32_e32 v24, 0x3fb8aa3b, v24
	v_mul_f32_e32 v22, v34, v22
	v_exp_f32_e32 v24, v24
	v_bfe_u32 v23, v22, 16, 1
	v_add3_u32 v22, v22, v23, s46
	ds_write_b16_d16_hi v19, v22 offset:37440
	v_lshlrev_b32_e32 v22, 16, v25
	v_mul_f32_e32 v22, v24, v22
	v_sub_f32_e32 v24, v37, v45
	v_mul_f32_e32 v24, 0x3fb8aa3b, v24
	v_exp_f32_e32 v24, v24
	v_bfe_u32 v23, v22, 16, 1
	v_add3_u32 v22, v22, v23, s46
	ds_write_b16_d16_hi v19, v22 offset:37584
	v_and_b32_e32 v22, 0xffff0000, v25
	v_mul_f32_e32 v22, v24, v22
	v_bfe_u32 v23, v22, 16, 1
	v_add3_u32 v22, v22, v23, s46
	s_waitcnt lgkmcnt(3)
	v_sub_f32_e32 v23, v30, v38
	v_mul_f32_e32 v23, 0x3fb8aa3b, v23
	v_exp_f32_e32 v23, v23
	s_waitcnt vmcnt(10)
; __device__ __forceinline__ bf16_t f2bf(float f) { return (bf16_t)f2bf_u(f); }
; __device__ __forceinline__ float bf_lo(unsigned u) { return __uint_as_float(u << 16); }
; __device__ __forceinline__ float bf_hi(unsigned u) { return __uint_as_float(u & 0xffff0000u); }
; __device__ void phaseG1_task(const Params& p, int task, char* lds) {
;     ...
;     {
;         const int s = lane, dc = wave * 32;
;         const bf16_t* kp = Z + (size_t)(tok0 + s) * ZC + ZK_G + h * 128 + dc;
; #pragma unroll
;         for (int v4 = 0; v4 < 4; v4++) {
;             const u32x4 kv = *(const u32x4*)(kp + v4 * 8);
;             const unsigned kw[4] = {kv.x, kv.y, kv.z, kv.w};
; #pragma unroll
;             for (int j = 0; j < 8; j++) {
;                 const int d = dc + v4 * 8 + j;
;                 const float kval = (j & 1) ? bf_hi(kw[j >> 1]) : bf_lo(kw[j >> 1]);
;                 klT[d * 72 + s] = f2bf(kval * __expf(bc[63 * 128 + d] - bc[s * 128 + d]));
;             }
;         }
;     }
;     for (int eh = 0; eh < 2; eh++) {
;         __syncthreads();
	v_lshlrev_b32_e32 v24, 16, v26
	ds_read_b128 v[34:37], v16 offset:32304
	ds_read_b128 v[42:45], v17 offset:48
	ds_write_b16_d16_hi v19, v22 offset:37728
	v_mul_f32_e32 v23, v23, v24
	v_bfe_u32 v24, v23, 16, 1
	v_add3_u32 v23, v23, v24, s46
	v_sub_f32_e32 v24, v31, v39
	v_or_b32_e32 v22, 8, v14
	v_mul_f32_e32 v24, 0x3fb8aa3b, v24
	v_mul_u32_u24_e32 v22, 0x48, v22
	v_exp_f32_e32 v24, v24
	v_or_b32_e32 v22, v22, v18
	v_lshl_add_u32 v22, v22, 1, s33
	v_sub_f32_e32 v25, v32, v40
	ds_write_b16_d16_hi v22, v23 offset:36864
	v_and_b32_e32 v23, 0xffff0000, v26
	v_mul_f32_e32 v25, 0x3fb8aa3b, v25
	v_mul_f32_e32 v23, v24, v23
	v_exp_f32_e32 v25, v25
	v_bfe_u32 v24, v23, 16, 1
	v_add3_u32 v23, v23, v24, s46
	ds_write_b16_d16_hi v19, v23 offset:38016
	v_lshlrev_b32_e32 v23, 16, v27
	v_mul_f32_e32 v23, v25, v23
	v_sub_f32_e32 v25, v33, v41
	v_mul_f32_e32 v25, 0x3fb8aa3b, v25
	v_exp_f32_e32 v25, v25
	v_bfe_u32 v24, v23, 16, 1
	v_add3_u32 v23, v23, v24, s46
	ds_write_b16_d16_hi v19, v23 offset:38160
	v_and_b32_e32 v23, 0xffff0000, v27
	v_mul_f32_e32 v23, v25, v23
	s_waitcnt lgkmcnt(4)
	v_sub_f32_e32 v25, v34, v42
	v_mul_f32_e32 v25, 0x3fb8aa3b, v25
	v_exp_f32_e32 v25, v25
	v_bfe_u32 v24, v23, 16, 1
	v_add3_u32 v23, v23, v24, s46
	ds_write_b16_d16_hi v19, v23 offset:38304
	v_lshlrev_b32_e32 v23, 16, v28
	v_mul_f32_e32 v23, v25, v23
	v_sub_f32_e32 v25, v35, v43
	v_mul_f32_e32 v25, 0x3fb8aa3b, v25
	v_exp_f32_e32 v25, v25
	v_bfe_u32 v24, v23, 16, 1
	v_add3_u32 v23, v23, v24, s46
	ds_write_b16_d16_hi v19, v23 offset:38448
	v_and_b32_e32 v23, 0xffff0000, v28
	v_mul_f32_e32 v23, v25, v23
	v_sub_f32_e32 v25, v36, v44
	v_mul_f32_e32 v25, 0x3fb8aa3b, v25
	v_exp_f32_e32 v25, v25
	v_bfe_u32 v24, v23, 16, 1
	v_add3_u32 v23, v23, v24, s46
	ds_write_b16_d16_hi v19, v23 offset:38592
	v_lshlrev_b32_e32 v23, 16, v29
	v_mul_f32_e32 v23, v25, v23
	v_sub_f32_e32 v25, v37, v45
	v_mul_f32_e32 v25, 0x3fb8aa3b, v25
	v_exp_f32_e32 v25, v25
	v_bfe_u32 v24, v23, 16, 1
	v_add3_u32 v23, v23, v24, s46
	ds_write_b16_d16_hi v19, v23 offset:38736
	v_and_b32_e32 v23, 0xffff0000, v29
	v_mul_f32_e32 v23, v25, v23
	ds_read_b128 v[24:27], v16 offset:32320
	ds_read_b128 v[28:31], v17 offset:64
	v_bfe_u32 v32, v23, 16, 1
	v_add3_u32 v23, v23, v32, s46
	ds_read_b128 v[32:35], v16 offset:32336
	ds_read_b128 v[36:39], v17 offset:80
	ds_write_b16_d16_hi v19, v23 offset:38880
	s_waitcnt lgkmcnt(3)
	v_sub_f32_e32 v24, v24, v28
	v_sub_f32_e32 v25, v25, v29
	v_mul_f32_e32 v24, 0x3fb8aa3b, v24
	v_mul_f32_e32 v25, 0x3fb8aa3b, v25
	v_exp_f32_e32 v24, v24
	v_exp_f32_e32 v25, v25
	v_or_b32_e32 v23, 16, v14
	s_waitcnt vmcnt(8)
	v_lshlrev_b32_e32 v28, 16, v4
	v_and_b32_e32 v4, 0xffff0000, v4
	v_mul_f32_e32 v24, v24, v28
	v_mul_u32_u24_e32 v23, 0x48, v23
	v_mul_f32_e32 v4, v25, v4
	v_sub_f32_e32 v25, v26, v30
	v_bfe_u32 v28, v24, 16, 1
	v_or_b32_e32 v23, v23, v18
	v_mul_f32_e32 v25, 0x3fb8aa3b, v25
	v_add3_u32 v24, v24, v28, s46
	v_lshl_add_u32 v23, v23, 1, s33
	v_exp_f32_e32 v25, v25
	ds_write_b16_d16_hi v23, v24 offset:36864
	v_bfe_u32 v24, v4, 16, 1
	v_add3_u32 v4, v4, v24, s46
	ds_write_b16_d16_hi v19, v4 offset:39168
	v_lshlrev_b32_e32 v4, 16, v5
	v_mul_f32_e32 v4, v25, v4
	v_sub_f32_e32 v25, v27, v31
	v_mul_f32_e32 v25, 0x3fb8aa3b, v25
	v_exp_f32_e32 v25, v25
	v_bfe_u32 v24, v4, 16, 1
	v_add3_u32 v4, v4, v24, s46
	s_waitcnt lgkmcnt(3)
	v_sub_f32_e32 v24, v32, v36
	ds_write_b16_d16_hi v19, v4 offset:39312
	v_and_b32_e32 v4, 0xffff0000, v5
	v_mul_f32_e32 v24, 0x3fb8aa3b, v24
	v_mul_f32_e32 v4, v25, v4
	v_exp_f32_e32 v24, v24
	v_bfe_u32 v5, v4, 16, 1
	v_add3_u32 v4, v4, v5, s46
	ds_write_b16_d16_hi v19, v4 offset:39456
	v_lshlrev_b32_e32 v4, 16, v6
	v_mul_f32_e32 v4, v24, v4
	v_sub_f32_e32 v24, v33, v37
	v_mul_f32_e32 v24, 0x3fb8aa3b, v24
	v_bfe_u32 v5, v4, 16, 1
	v_exp_f32_e32 v24, v24
	v_add3_u32 v4, v4, v5, s46
	ds_write_b16_d16_hi v19, v4 offset:39600
	v_and_b32_e32 v4, 0xffff0000, v6
	v_sub_f32_e32 v6, v34, v38
	v_mul_f32_e32 v6, 0x3fb8aa3b, v6
	v_mul_f32_e32 v4, v24, v4
	v_exp_f32_e32 v6, v6
	v_bfe_u32 v5, v4, 16, 1
	v_add3_u32 v4, v4, v5, s46
	ds_write_b16_d16_hi v19, v4 offset:39744
	v_lshlrev_b32_e32 v4, 16, v7
	v_mul_f32_e32 v4, v6, v4
	v_sub_f32_e32 v6, v35, v39
	v_mul_f32_e32 v6, 0x3fb8aa3b, v6
	v_exp_f32_e32 v6, v6
	v_bfe_u32 v5, v4, 16, 1
	v_add3_u32 v4, v4, v5, s46
	ds_write_b16_d16_hi v19, v4 offset:39888
	v_and_b32_e32 v4, 0xffff0000, v7
	v_mul_f32_e32 v28, v6, v4
	ds_read_b128 v[4:7], v16 offset:32352
	ds_read_b128 v[24:27], v17 offset:96
	v_bfe_u32 v29, v28, 16, 1
	v_add3_u32 v36, v28, v29, s46
	ds_read_b128 v[28:31], v16 offset:32368
	ds_read_b128 v[32:35], v17 offset:112
	v_or_b32_e32 v17, 24, v14
	s_waitcnt lgkmcnt(2)
	v_sub_f32_e32 v4, v4, v24
	v_sub_f32_e32 v5, v5, v25
	v_mul_f32_e32 v4, 0x3fb8aa3b, v4
	v_mul_f32_e32 v5, 0x3fb8aa3b, v5
	v_exp_f32_e32 v4, v4
	v_exp_f32_e32 v5, v5
	v_lshlrev_b32_e32 v24, 16, v0
	v_and_b32_e32 v0, 0xffff0000, v0
	v_mul_f32_e32 v4, v4, v24
	v_mul_u32_u24_e32 v17, 0x48, v17
	v_mul_f32_e32 v0, v5, v0
	v_sub_f32_e32 v5, v6, v26
	v_bfe_u32 v24, v4, 16, 1
	v_or_b32_e32 v17, v17, v18
	v_mul_f32_e32 v5, 0x3fb8aa3b, v5
	v_add3_u32 v4, v4, v24, s46
	v_lshl_add_u32 v124, v17, 1, s33
	v_exp_f32_e32 v5, v5
	ds_write_b16_d16_hi v19, v36 offset:40032
	ds_write_b16_d16_hi v124, v4 offset:36864
	v_bfe_u32 v4, v0, 16, 1
	v_add3_u32 v0, v0, v4, s46
	ds_write_b16_d16_hi v19, v0 offset:40320
	v_lshlrev_b32_e32 v0, 16, v1
	v_mul_f32_e32 v0, v5, v0
	v_sub_f32_e32 v5, v7, v27
	v_mul_f32_e32 v5, 0x3fb8aa3b, v5
	v_exp_f32_e32 v5, v5
	v_bfe_u32 v4, v0, 16, 1
	v_add3_u32 v0, v0, v4, s46
	s_waitcnt lgkmcnt(3)
	v_sub_f32_e32 v4, v28, v32
	ds_write_b16_d16_hi v19, v0 offset:40464
	v_and_b32_e32 v0, 0xffff0000, v1
	v_mul_f32_e32 v4, 0x3fb8aa3b, v4
	v_mul_f32_e32 v0, v5, v0
	v_exp_f32_e32 v4, v4
	v_bfe_u32 v1, v0, 16, 1
	v_add3_u32 v0, v0, v1, s46
	ds_write_b16_d16_hi v19, v0 offset:40608
	v_lshlrev_b32_e32 v0, 16, v2
	v_mul_f32_e32 v0, v4, v0
	v_sub_f32_e32 v4, v29, v33
	v_mul_f32_e32 v4, 0x3fb8aa3b, v4
	v_bfe_u32 v1, v0, 16, 1
	v_exp_f32_e32 v4, v4
	v_add3_u32 v0, v0, v1, s46
	ds_write_b16_d16_hi v19, v0 offset:40752
	v_and_b32_e32 v0, 0xffff0000, v2
	v_sub_f32_e32 v2, v30, v34
	v_mul_f32_e32 v2, 0x3fb8aa3b, v2
	v_mul_f32_e32 v0, v4, v0
	v_exp_f32_e32 v2, v2
	v_bfe_u32 v1, v0, 16, 1
	v_add3_u32 v0, v0, v1, s46
	ds_write_b16_d16_hi v19, v0 offset:40896
	v_lshlrev_b32_e32 v0, 16, v3
	v_mul_f32_e32 v0, v2, v0
	v_sub_f32_e32 v2, v31, v35
	v_mul_f32_e32 v2, 0x3fb8aa3b, v2
	v_exp_f32_e32 v2, v2
	v_bfe_u32 v1, v0, 16, 1
	v_add3_u32 v0, v0, v1, s46
	ds_write_b16_d16_hi v19, v0 offset:41040
	v_and_b32_e32 v0, 0xffff0000, v3
	v_mul_f32_e32 v0, v2, v0
	v_bfe_u32 v1, v0, 16, 1
	v_add3_u32 v0, v0, v1, s46
	ds_write_b16_d16_hi v19, v0 offset:41184
	v_lshl_add_u64 v[0:1], v[10:11], 0, s[18:19]
	v_lshl_add_u64 v[0:1], v[0:1], 0, v[8:9]
	s_waitcnt lgkmcnt(0)
	s_barrier
; __device__ __forceinline__ f32x4 mfma16(bf16x8 a, bf16x8 b, f32x4 c) { return __builtin_amdgcn_mfma_f32_16x16x32_bf16(a, b, c, 0, 0, 0); }
; __device__ void phaseG1_task(const Params& p, int task, char* lds) {
;     ...
;         {
;             const int s = lane, ec = wave * 32;
;             const bf16_t* vp = Z + (size_t)(tok0 + s) * ZC + ZV_G + h * 256 + eh * 128 + ec;
; #pragma unroll
;             for (int v4 = 0; v4 < 4; v4++) {
;                 const u32x4 vv = *(const u32x4*)(vp + v4 * 8);
;                 const unsigned vw[4] = {vv.x, vv.y, vv.z, vv.w};
; #pragma unroll
;                 for (int j = 0; j < 8; j++) vT[(ec + v4 * 8 + j) * 72 + s] = (bf16_t)((j & 1) ? (vw[j >> 1] >> 16) : (vw[j >> 1] & 0xffffu));
;             }
;         }
;         __syncthreads();
;         f32x4 acc[8][2];
; #pragma unroll
;         for (int dt = 0; dt < 8; dt++) { acc[dt][0] = (f32x4){0.f, 0.f, 0.f, 0.f}; acc[dt][1] = (f32x4){0.f, 0.f, 0.f, 0.f}; }
; #pragma unroll
;         for (int ks = 0; ks < 2; ks++) {
;             bf16x8 bv[2];
; #pragma unroll
;             for (int x = 0; x < 2; x++) bv[x] = ld_frag(vT + ((2 * wave + x) * 16 + r) * 72 + ks * 32 + q * 8);
; #pragma unroll
;             for (int dt = 0; dt < 8; dt++) {
;                 const bf16x8 a = ld_frag(klT + (dt * 16 + r) * 72 + ks * 32 + q * 8);
; #pragma unroll
;                 for (int x = 0; x < 2; x++) acc[dt][x] = mfma16(a, bv[x], acc[dt][x]);
;             }
;         }
; #pragma unroll
;         for (int dt = 0; dt < 8; dt++)
; #pragma unroll
;             for (int x = 0; x < 2; x++) {
;                 const int e = eh * 128 + (2 * wave + x) * 16 + r, d = dt * 16 + 4 * q;
;                 const f32x4 v = acc[dt][x];
;                 *(u32x2*)(L + ((size_t)task * 256 + e) * 128 + d) = (u32x2){pack2(v[0], v[1]), pack2(v[2], v[3])};
;             }
	v_mul_u32_u24_e32 v8, 0x8c, v14
	v_and_b32_e32 v6, 15, v12
	v_and_b32_e32 v7, 48, v12
	v_add3_u32 v125, v16, v8, v15
	v_add_u32_e32 v7, s33, v7
	v_or_b32_e32 v12, v14, v6
	v_and_b32_e32 v8, 24, v13
	s_waitcnt vmcnt(7)
	ds_write_b16 v21, v130 offset:55296
	ds_write_b16_d16_hi v125, v130 offset:55440
	ds_write_b16 v125, v131 offset:55584
	ds_write_b16_d16_hi v125, v131 offset:55728
	ds_write_b16 v125, v132 offset:55872
	ds_write_b16_d16_hi v125, v132 offset:56016
	ds_write_b16 v125, v133 offset:56160
	ds_write_b16_d16_hi v125, v133 offset:56304
	s_waitcnt vmcnt(6)
	ds_write_b16 v22, v134 offset:55296
	ds_write_b16_d16_hi v125, v134 offset:56592
	ds_write_b16 v125, v135 offset:56736
	ds_write_b16_d16_hi v125, v135 offset:56880
	ds_write_b16 v125, v136 offset:57024
	ds_write_b16_d16_hi v125, v136 offset:57168
	ds_write_b16 v125, v137 offset:57312
	ds_write_b16_d16_hi v125, v137 offset:57456
	s_waitcnt vmcnt(5)
	ds_write_b16 v23, v138 offset:55296
	ds_write_b16_d16_hi v125, v138 offset:57744
	ds_write_b16 v125, v139 offset:57888
	ds_write_b16_d16_hi v125, v139 offset:58032
	ds_write_b16 v125, v140 offset:58176
	ds_write_b16_d16_hi v125, v140 offset:58320
	ds_write_b16 v125, v141 offset:58464
	ds_write_b16_d16_hi v125, v141 offset:58608
	s_waitcnt vmcnt(4)
	ds_write_b16 v124, v142 offset:55296
	ds_write_b16_d16_hi v125, v142 offset:58896
	ds_write_b16 v125, v143 offset:59040
	ds_write_b16_d16_hi v125, v143 offset:59184
	ds_write_b16 v125, v144 offset:59328
	ds_write_b16_d16_hi v125, v144 offset:59472
	ds_write_b16 v125, v145 offset:59616
	ds_write_b16_d16_hi v125, v145 offset:59760
	v_mul_u32_u24_e32 v2, 0x48, v6
	v_lshl_add_u32 v126, v2, 1, v7
	s_waitcnt vmcnt(0) lgkmcnt(0)
	s_barrier
	ds_read_b128 v[2:5], v126 offset:36864
	v_mul_u32_u24_e32 v6, 0x48, v12
	v_lshl_add_u32 v127, v6, 1, v7
	ds_read_b128 v[14:17], v127 offset:55296
	ds_read_b128 v[24:27], v127 offset:55360
	ds_read_b128 v[28:31], v126 offset:36928
	ds_read_b128 v[36:39], v127 offset:57600
	ds_read_b128 v[40:43], v127 offset:57664
	ds_read_b128 v[44:47], v126 offset:39168
	ds_read_b128 v[48:51], v126 offset:39232
	s_waitcnt lgkmcnt(6)
	v_mfma_f32_16x16x32_bf16 v[32:35], v[2:5], v[14:17], 0
	ds_read_b128 v[56:59], v126 offset:41472
	ds_read_b128 v[60:63], v126 offset:41536
	ds_read_b128 v[68:71], v126 offset:43776
	ds_read_b128 v[72:75], v126 offset:43840
	ds_read_b128 v[80:83], v126 offset:46080
	ds_read_b128 v[84:87], v126 offset:46144
	s_waitcnt lgkmcnt(9)
	v_mfma_f32_16x16x32_bf16 v[2:5], v[2:5], v[36:39], 0
	ds_read_b128 v[92:95], v126 offset:48384
	ds_read_b128 v[96:99], v126 offset:48448
	ds_read_b128 v[104:107], v126 offset:50688
	ds_read_b128 v[108:111], v126 offset:50752
	ds_read_b128 v[116:119], v126 offset:52992
	ds_read_b128 v[120:123], v126 offset:53056
	s_waitcnt lgkmcnt(13)
	v_mfma_f32_16x16x32_bf16 v[52:55], v[44:47], v[14:17], 0
	v_mfma_f32_16x16x32_bf16 v[44:47], v[44:47], v[36:39], 0
	s_waitcnt lgkmcnt(11)
	v_mfma_f32_16x16x32_bf16 v[64:67], v[56:59], v[14:17], 0
	v_mfma_f32_16x16x32_bf16 v[32:35], v[28:31], v[24:27], v[32:35]
	v_mfma_f32_16x16x32_bf16 v[56:59], v[56:59], v[36:39], 0
	v_mfma_f32_16x16x32_bf16 v[4:7], v[28:31], v[40:43], v[2:5]
	s_nop 5
	v_cvt_pk_bf16_f32 v11, v34, v35
	v_mov_b32_e32 v35, v9
	v_cvt_pk_bf16_f32 v10, v32, v33
	s_waitcnt lgkmcnt(9)
	v_mfma_f32_16x16x32_bf16 v[76:79], v[68:71], v[14:17], 0
	v_lshl_add_u64 v[2:3], s[4:5], 0, v[8:9]
	v_lshlrev_b32_e32 v8, 8, v12
	v_or_b32_e32 v34, 0x1000, v8
	v_mfma_f32_16x16x32_bf16 v[28:31], v[48:51], v[24:27], v[52:55]
	v_cvt_pk_bf16_f32 v4, v4, v5
	v_cvt_pk_bf16_f32 v5, v6, v7
	v_lshl_add_u64 v[6:7], v[2:3], 0, v[34:35]
	v_mfma_f32_16x16x32_bf16 v[68:71], v[68:71], v[36:39], 0
	v_lshl_add_u64 v[32:33], v[2:3], 0, v[8:9]
	global_store_dwordx2 v[6:7], v[4:5], off
	v_lshl_add_u64 v[4:5], v[2:3], 0, 32
	v_mfma_f32_16x16x32_bf16 v[44:47], v[48:51], v[40:43], v[44:47]
	v_cvt_pk_bf16_f32 v6, v28, v29
	v_cvt_pk_bf16_f32 v7, v30, v31
	global_store_dwordx2 v[32:33], v[10:11], off
	s_waitcnt lgkmcnt(7)
	v_mfma_f32_16x16x32_bf16 v[88:91], v[80:83], v[14:17], 0
	global_store_dwordx2 v[32:33], v[6:7], off offset:32
	s_nop 1
	v_cvt_pk_bf16_f32 v6, v44, v45
	v_cvt_pk_bf16_f32 v7, v46, v47
	v_mfma_f32_16x16x32_bf16 v[48:51], v[60:63], v[24:27], v[64:67]
	v_lshl_add_u64 v[10:11], v[4:5], 0, v[34:35]
	global_store_dwordx2 v[10:11], v[6:7], off
	v_lshl_add_u64 v[6:7], v[2:3], 0, 64
	v_mfma_f32_16x16x32_bf16 v[80:83], v[80:83], v[36:39], 0
	v_lshl_add_u64 v[12:13], v[6:7], 0, v[34:35]
	s_nop 2
	v_cvt_pk_bf16_f32 v10, v48, v49
	v_cvt_pk_bf16_f32 v11, v50, v51
	v_mfma_f32_16x16x32_bf16 v[52:55], v[60:63], v[40:43], v[56:59]
	global_store_dwordx2 v[32:33], v[10:11], off offset:64
	s_waitcnt lgkmcnt(5)
	v_mfma_f32_16x16x32_bf16 v[100:103], v[92:95], v[14:17], 0
	v_mfma_f32_16x16x32_bf16 v[56:59], v[72:75], v[24:27], v[76:79]
	s_nop 3
	v_cvt_pk_bf16_f32 v10, v52, v53
	v_cvt_pk_bf16_f32 v11, v54, v55
	global_store_dwordx2 v[12:13], v[10:11], off
	v_mfma_f32_16x16x32_bf16 v[92:95], v[92:95], v[36:39], 0
	v_lshl_add_u64 v[10:11], v[2:3], 0, s[22:23]
	v_cvt_pk_bf16_f32 v12, v56, v57
	v_cvt_pk_bf16_f32 v13, v58, v59
	s_waitcnt lgkmcnt(3)
	v_mfma_f32_16x16x32_bf16 v[112:115], v[104:107], v[14:17], 0
	global_store_dwordx2 v[32:33], v[12:13], off offset:96
	s_waitcnt lgkmcnt(1)
	v_mfma_f32_16x16x32_bf16 v[14:17], v[116:119], v[14:17], 0
	v_mfma_f32_16x16x32_bf16 v[60:63], v[72:75], v[40:43], v[68:71]
	v_mfma_f32_16x16x32_bf16 v[64:67], v[84:87], v[24:27], v[88:91]
	v_mfma_f32_16x16x32_bf16 v[104:107], v[104:107], v[36:39], 0
	s_nop 5
	v_cvt_pk_bf16_f32 v12, v60, v61
	v_cvt_pk_bf16_f32 v13, v62, v63
	v_mfma_f32_16x16x32_bf16 v[68:71], v[84:87], v[40:43], v[80:83]
	v_mfma_f32_16x16x32_bf16 v[72:75], v[96:99], v[24:27], v[100:103]
	v_mfma_f32_16x16x32_bf16 v[36:39], v[116:119], v[36:39], 0
	v_mfma_f32_16x16x32_bf16 v[76:79], v[96:99], v[40:43], v[92:95]
	v_mfma_f32_16x16x32_bf16 v[80:83], v[108:111], v[24:27], v[112:115]
	s_waitcnt lgkmcnt(0)
; __device__ void phaseG1_task(const Params& p, int task, char* lds) {
;     ...
;         {
;             const int s = lane, ec = wave * 32;
;             const bf16_t* vp = Z + (size_t)(tok0 + s) * ZC + ZV_G + h * 256 + eh * 128 + ec;
; #pragma unroll
;             for (int v4 = 0; v4 < 4; v4++) {
;                 const u32x4 vv = *(const u32x4*)(vp + v4 * 8);
;                 const unsigned vw[4] = {vv.x, vv.y, vv.z, vv.w};
; #pragma unroll
;                 for (int j = 0; j < 8; j++) vT[(ec + v4 * 8 + j) * 72 + s] = (bf16_t)((j & 1) ? (vw[j >> 1] >> 16) : (vw[j >> 1] & 0xffffu));
;             }
;         }
;         __syncthreads();
;     ...
; #pragma unroll
;         for (int dt = 0; dt < 8; dt++)
; #pragma unroll
;             for (int x = 0; x < 2; x++) {
;                 const int e = eh * 128 + (2 * wave + x) * 16 + r, d = dt * 16 + 4 * q;
;                 const f32x4 v = acc[dt][x];
;                 *(u32x2*)(L + ((size_t)task * 256 + e) * 128 + d) = (u32x2){pack2(v[0], v[1]), pack2(v[2], v[3])};
;             }
	v_mfma_f32_16x16x32_bf16 v[24:27], v[120:123], v[24:27], v[14:17]
	s_nop 2
	v_lshl_add_u64 v[14:15], v[10:11], 0, v[34:35]
	global_store_dwordx2 v[14:15], v[12:13], off
	v_lshl_add_u64 v[12:13], v[2:3], 0, s[24:25]
	v_cvt_pk_bf16_f32 v14, v64, v65
	v_cvt_pk_bf16_f32 v15, v66, v67
	v_mfma_f32_16x16x32_bf16 v[84:87], v[108:111], v[40:43], v[104:107]
	global_store_dwordx2 v[32:33], v[14:15], off offset:128
	v_cvt_pk_bf16_f32 v14, v68, v69
	v_cvt_pk_bf16_f32 v15, v70, v71
	v_lshl_add_u64 v[16:17], v[12:13], 0, v[34:35]
	global_store_dwordx2 v[16:17], v[14:15], off
	v_lshl_add_u64 v[14:15], v[2:3], 0, s[26:27]
	v_cvt_pk_bf16_f32 v16, v72, v73
	v_cvt_pk_bf16_f32 v17, v74, v75
	v_mfma_f32_16x16x32_bf16 v[36:39], v[120:123], v[40:43], v[36:39]
	global_store_dwordx2 v[32:33], v[16:17], off offset:160
	v_cvt_pk_bf16_f32 v16, v76, v77
	v_cvt_pk_bf16_f32 v17, v78, v79
	v_lshl_add_u64 v[18:19], v[14:15], 0, v[34:35]
	global_store_dwordx2 v[18:19], v[16:17], off
	v_lshl_add_u64 v[16:17], v[2:3], 0, s[28:29]
	v_cvt_pk_bf16_f32 v18, v80, v81
	v_cvt_pk_bf16_f32 v19, v82, v83
	global_store_dwordx2 v[32:33], v[18:19], off offset:192
	v_cvt_pk_bf16_f32 v18, v84, v85
	v_cvt_pk_bf16_f32 v19, v86, v87
	v_lshl_add_u64 v[28:29], v[16:17], 0, v[34:35]
	global_store_dwordx2 v[28:29], v[18:19], off
	v_lshl_add_u64 v[18:19], v[2:3], 0, s[30:31]
	v_cvt_pk_bf16_f32 v24, v24, v25
	v_cvt_pk_bf16_f32 v25, v26, v27
	global_store_dwordx2 v[32:33], v[24:25], off offset:224
	v_cvt_pk_bf16_f32 v24, v36, v37
	v_cvt_pk_bf16_f32 v25, v38, v39
	v_lshl_add_u64 v[26:27], v[18:19], 0, v[34:35]
	global_store_dwordx2 v[26:27], v[24:25], off
	s_barrier
	ds_write_b16 v21, v146 offset:55296
	ds_write_b16_d16_hi v125, v146 offset:55440
	ds_write_b16 v125, v147 offset:55584
	ds_write_b16_d16_hi v125, v147 offset:55728
	ds_write_b16 v125, v148 offset:55872
	ds_write_b16_d16_hi v125, v148 offset:56016
	ds_write_b16 v125, v149 offset:56160
	ds_write_b16_d16_hi v125, v149 offset:56304
	ds_write_b16 v22, v150 offset:55296
	ds_write_b16_d16_hi v125, v150 offset:56592
	ds_write_b16 v125, v151 offset:56736
	ds_write_b16_d16_hi v125, v151 offset:56880
	ds_write_b16 v125, v152 offset:57024
	ds_write_b16_d16_hi v125, v152 offset:57168
	ds_write_b16 v125, v153 offset:57312
	ds_write_b16_d16_hi v125, v153 offset:57456
	ds_write_b16 v23, v154 offset:55296
	ds_write_b16_d16_hi v125, v154 offset:57744
	ds_write_b16 v125, v155 offset:57888
	ds_write_b16_d16_hi v125, v155 offset:58032
	ds_write_b16 v125, v156 offset:58176
	ds_write_b16_d16_hi v125, v156 offset:58320
	ds_write_b16 v125, v157 offset:58464
	ds_write_b16_d16_hi v125, v157 offset:58608
	ds_write_b16 v124, v160 offset:55296
	ds_write_b16_d16_hi v125, v160 offset:58896
	ds_write_b16 v125, v161 offset:59040
	ds_write_b16_d16_hi v125, v161 offset:59184
	ds_write_b16 v125, v162 offset:59328
	ds_write_b16_d16_hi v125, v162 offset:59472
	ds_write_b16 v125, v163 offset:59616
	ds_write_b16_d16_hi v125, v163 offset:59760
	s_waitcnt lgkmcnt(0)
	s_barrier
; __device__ __forceinline__ f32x4 mfma16(bf16x8 a, bf16x8 b, f32x4 c) { return __builtin_amdgcn_mfma_f32_16x16x32_bf16(a, b, c, 0, 0, 0); }
; __device__ void phaseG1_task(const Params& p, int task, char* lds) {
;     ...
;         f32x4 acc[8][2];
; #pragma unroll
;         for (int dt = 0; dt < 8; dt++) { acc[dt][0] = (f32x4){0.f, 0.f, 0.f, 0.f}; acc[dt][1] = (f32x4){0.f, 0.f, 0.f, 0.f}; }
; #pragma unroll
;         for (int ks = 0; ks < 2; ks++) {
;             bf16x8 bv[2];
; #pragma unroll
;             for (int x = 0; x < 2; x++) bv[x] = ld_frag(vT + ((2 * wave + x) * 16 + r) * 72 + ks * 32 + q * 8);
; #pragma unroll
;             for (int dt = 0; dt < 8; dt++) {
;                 const bf16x8 a = ld_frag(klT + (dt * 16 + r) * 72 + ks * 32 + q * 8);
; #pragma unroll
;                 for (int x = 0; x < 2; x++) acc[dt][x] = mfma16(a, bv[x], acc[dt][x]);
;             }
;         }
; #pragma unroll
;         for (int dt = 0; dt < 8; dt++)
; #pragma unroll
;             for (int x = 0; x < 2; x++) {
;                 const int e = eh * 128 + (2 * wave + x) * 16 + r, d = dt * 16 + 4 * q;
;                 const f32x4 v = acc[dt][x];
;                 *(u32x2*)(L + ((size_t)task * 256 + e) * 128 + d) = (u32x2){pack2(v[0], v[1]), pack2(v[2], v[3])};
;             }
;     }
;     __syncthreads();
	ds_read_b128 v[22:25], v126 offset:36864
	ds_read_b128 v[26:29], v127 offset:55296
	ds_read_b128 v[30:33], v127 offset:55360
	ds_read_b128 v[34:37], v126 offset:36928
	ds_read_b128 v[42:45], v127 offset:57600
	ds_read_b128 v[46:49], v127 offset:57664
	ds_read_b128 v[50:53], v126 offset:39168
	ds_read_b128 v[54:57], v126 offset:39232
	s_waitcnt lgkmcnt(6)
	v_mfma_f32_16x16x32_bf16 v[38:41], v[22:25], v[26:29], 0
	ds_read_b128 v[62:65], v126 offset:41472
	ds_read_b128 v[66:69], v126 offset:41536
	ds_read_b128 v[74:77], v126 offset:43776
	ds_read_b128 v[78:81], v126 offset:43840
	ds_read_b128 v[86:89], v126 offset:46080
	ds_read_b128 v[90:93], v126 offset:46144
	s_waitcnt lgkmcnt(9)
	v_mfma_f32_16x16x32_bf16 v[22:25], v[22:25], v[42:45], 0
	ds_read_b128 v[98:101], v126 offset:48384
	ds_read_b128 v[102:105], v126 offset:48448
	ds_read_b128 v[110:113], v126 offset:50688
	ds_read_b128 v[114:117], v126 offset:50752
	ds_read_b128 v[122:125], v126 offset:52992
	ds_read_b128 v[126:129], v126 offset:53056
	s_waitcnt lgkmcnt(13)
	v_mfma_f32_16x16x32_bf16 v[58:61], v[50:53], v[26:29], 0
	v_mfma_f32_16x16x32_bf16 v[50:53], v[50:53], v[42:45], 0
	v_mfma_f32_16x16x32_bf16 v[38:41], v[34:37], v[30:33], v[38:41]
	s_waitcnt lgkmcnt(11)
	v_mfma_f32_16x16x32_bf16 v[70:73], v[62:65], v[26:29], 0
	v_mfma_f32_16x16x32_bf16 v[62:65], v[62:65], v[42:45], 0
	s_nop 4
	v_cvt_pk_bf16_f32 v0, v38, v39
	v_or_b32_e32 v38, 0x8000, v8
	v_mov_b32_e32 v39, v9
	v_mfma_f32_16x16x32_bf16 v[22:25], v[34:37], v[46:49], v[22:25]
	v_cvt_pk_bf16_f32 v1, v40, v41
	v_lshl_add_u64 v[40:41], v[2:3], 0, v[38:39]
	v_or_b32_e32 v8, 0x9000, v8
	s_waitcnt lgkmcnt(9)
	v_mfma_f32_16x16x32_bf16 v[82:85], v[74:77], v[26:29], 0
	global_store_dwordx2 v[40:41], v[0:1], off
	s_nop 1
	v_cvt_pk_bf16_f32 v0, v22, v23
	v_cvt_pk_bf16_f32 v1, v24, v25
	v_mfma_f32_16x16x32_bf16 v[34:37], v[54:57], v[30:33], v[58:61]
	v_lshl_add_u64 v[2:3], v[2:3], 0, v[8:9]
	global_store_dwordx2 v[2:3], v[0:1], off
	v_lshl_add_u64 v[2:3], v[4:5], 0, v[38:39]
	v_mfma_f32_16x16x32_bf16 v[74:77], v[74:77], v[42:45], 0
	v_mfma_f32_16x16x32_bf16 v[50:53], v[54:57], v[46:49], v[50:53]
	s_nop 2
	v_cvt_pk_bf16_f32 v0, v34, v35
	v_cvt_pk_bf16_f32 v1, v36, v37
	global_store_dwordx2 v[2:3], v[0:1], off
	s_waitcnt lgkmcnt(7)
	v_mfma_f32_16x16x32_bf16 v[94:97], v[86:89], v[26:29], 0
	v_lshl_add_u64 v[2:3], v[4:5], 0, v[8:9]
	v_cvt_pk_bf16_f32 v0, v50, v51
	v_cvt_pk_bf16_f32 v1, v52, v53
	v_mfma_f32_16x16x32_bf16 v[54:57], v[66:69], v[30:33], v[70:73]
	global_store_dwordx2 v[2:3], v[0:1], off
	v_lshl_add_u64 v[2:3], v[6:7], 0, v[38:39]
	v_mfma_f32_16x16x32_bf16 v[86:89], v[86:89], v[42:45], 0
	v_mfma_f32_16x16x32_bf16 v[58:61], v[66:69], v[46:49], v[62:65]
	s_nop 3
	v_cvt_pk_bf16_f32 v0, v54, v55
	v_cvt_pk_bf16_f32 v1, v56, v57
	global_store_dwordx2 v[2:3], v[0:1], off
	s_waitcnt lgkmcnt(5)
	v_mfma_f32_16x16x32_bf16 v[106:109], v[98:101], v[26:29], 0
	v_lshl_add_u64 v[2:3], v[6:7], 0, v[8:9]
	v_cvt_pk_bf16_f32 v0, v58, v59
	v_cvt_pk_bf16_f32 v1, v60, v61
	v_mfma_f32_16x16x32_bf16 v[62:65], v[78:81], v[30:33], v[82:85]
	global_store_dwordx2 v[2:3], v[0:1], off
	v_lshl_add_u64 v[2:3], v[10:11], 0, v[38:39]
	v_mfma_f32_16x16x32_bf16 v[98:101], v[98:101], v[42:45], 0
	v_mfma_f32_16x16x32_bf16 v[66:69], v[78:81], v[46:49], v[74:77]
	s_nop 3
	v_cvt_pk_bf16_f32 v0, v62, v63
	v_cvt_pk_bf16_f32 v1, v64, v65
	global_store_dwordx2 v[2:3], v[0:1], off
	s_waitcnt lgkmcnt(3)
	v_mfma_f32_16x16x32_bf16 v[118:121], v[110:113], v[26:29], 0
	v_lshl_add_u64 v[2:3], v[10:11], 0, v[8:9]
	v_cvt_pk_bf16_f32 v0, v66, v67
	v_cvt_pk_bf16_f32 v1, v68, v69
	v_mfma_f32_16x16x32_bf16 v[70:73], v[90:93], v[30:33], v[94:97]
	global_store_dwordx2 v[2:3], v[0:1], off
	v_lshl_add_u64 v[2:3], v[12:13], 0, v[38:39]
	v_mfma_f32_16x16x32_bf16 v[110:113], v[110:113], v[42:45], 0
	v_mfma_f32_16x16x32_bf16 v[74:77], v[90:93], v[46:49], v[86:89]
	s_nop 3
	v_cvt_pk_bf16_f32 v0, v70, v71
	v_cvt_pk_bf16_f32 v1, v72, v73
	global_store_dwordx2 v[2:3], v[0:1], off
	s_waitcnt lgkmcnt(1)
	v_mfma_f32_16x16x32_bf16 v[26:29], v[122:125], v[26:29], 0
	v_lshl_add_u64 v[2:3], v[12:13], 0, v[8:9]
	v_cvt_pk_bf16_f32 v0, v74, v75
	v_cvt_pk_bf16_f32 v1, v76, v77
	v_mfma_f32_16x16x32_bf16 v[78:81], v[102:105], v[30:33], v[106:109]
	global_store_dwordx2 v[2:3], v[0:1], off
	v_lshl_add_u64 v[2:3], v[14:15], 0, v[38:39]
	v_mfma_f32_16x16x32_bf16 v[42:45], v[122:125], v[42:45], 0
	v_mfma_f32_16x16x32_bf16 v[82:85], v[102:105], v[46:49], v[98:101]
	s_nop 3
	v_cvt_pk_bf16_f32 v0, v78, v79
	v_cvt_pk_bf16_f32 v1, v80, v81
	global_store_dwordx2 v[2:3], v[0:1], off
	v_mfma_f32_16x16x32_bf16 v[86:89], v[114:117], v[30:33], v[118:121]
	v_lshl_add_u64 v[2:3], v[14:15], 0, v[8:9]
	v_cvt_pk_bf16_f32 v0, v82, v83
	v_cvt_pk_bf16_f32 v1, v84, v85
	v_mfma_f32_16x16x32_bf16 v[90:93], v[114:117], v[46:49], v[110:113]
	global_store_dwordx2 v[2:3], v[0:1], off
	s_nop 2
	v_cvt_pk_bf16_f32 v0, v86, v87
	v_cvt_pk_bf16_f32 v1, v88, v89
	s_waitcnt lgkmcnt(0)
	v_mfma_f32_16x16x32_bf16 v[26:29], v[126:129], v[30:33], v[26:29]
	v_lshl_add_u64 v[2:3], v[16:17], 0, v[38:39]
	global_store_dwordx2 v[2:3], v[0:1], off
	v_cvt_pk_bf16_f32 v0, v90, v91
	v_mfma_f32_16x16x32_bf16 v[30:33], v[126:129], v[46:49], v[42:45]
	v_cvt_pk_bf16_f32 v1, v92, v93
	v_lshl_add_u64 v[2:3], v[16:17], 0, v[8:9]
	global_store_dwordx2 v[2:3], v[0:1], off
	s_nop 0
	v_cvt_pk_bf16_f32 v0, v26, v27
	v_cvt_pk_bf16_f32 v1, v28, v29
	v_lshl_add_u64 v[2:3], v[18:19], 0, v[38:39]
	global_store_dwordx2 v[2:3], v[0:1], off
	v_cvt_pk_bf16_f32 v0, v30, v31
	v_cvt_pk_bf16_f32 v1, v32, v33
	v_lshl_add_u64 v[2:3], v[18:19], 0, v[8:9]
	global_store_dwordx2 v[2:3], v[0:1], off
	s_barrier
	s_cbranch_scc1 .LBB0_387
